# attention: two register staging sets with two-block K/V lookahead (SADDR addressing), PV loop unrolled with 8-deep LDS read ring
# speedup vs baseline: 1.0094x; 1.0006x over previous
; #define LAS __attribute__((address_space(3)))
; #define LOADK(i) do { _Pragma("unroll") for (int j = 0; j < 4; ++j) st[j] = *(const u32x4*)(kbase + ((i) * 64 + j * 16) * 1024 + koff); } while (0)
; #define LOADV(i) do { _Pragma("unroll") for (int j = 0; j < 4; ++j) st[j] = *(const u32x4*)(vbase + (j * 64 * 256 + (i) * 64) + voff); } while (0)
; #define STOREK() do { _Pragma("unroll") for (int j = 0; j < 4; ++j) *(LAS u32x4*)(kst + j * 16 * 528) = st[j]; } while (0)
; __device__ __forceinline__ void ph_attn(const Params& p, LAS unsigned char* lds) {
;     ...
;         const bf16_t* kbase = kb + (size_t)kvb * 256 * 1024 + h * 256; const bf16_t* vbase = vt + ((size_t)kvb * 1024 + h * 256) * 256;
;     ...
;         f32x4 sc[16];
;         LOADK(0);
; #pragma unroll
;         for (int i = 0; i < 4; ++i) {
;             __syncthreads(); STOREK(); __syncthreads();
;             if (i < 3) LOADK(i + 1); else LOADV(0);
;             if (active) {
; #pragma unroll
;                 for (int sub = 0; sub < 4; ++sub) {
;                     f32x4 a = {0.f, 0.f, 0.f, 0.f};
; #pragma unroll
;                     for (int ks = 0; ks < 8; ++ks) {
;                         const bf16x8 kf = *(const LAS bf16x8*)(krd + sub * 16 * 528 + ks * 64);
;                         a = __builtin_amdgcn_mfma_f32_16x16x32_bf16(kf, qf[ks], a, 0, 0, 0);
;                     }
;                     sc[i * 4 + sub] = a;
;                 }
;             }
;         }
.LBB0_1092:
	s_ashr_i32 s5, s4, 31
	s_lshl_b64 s[16:17], s[4:5], 19
	s_add_u32 s18, s3, s16
	s_addc_u32 s19, s14, s17
	s_lshl_b64 s[4:5], s[10:11], 1
	s_add_u32 s98, s18, s4
	s_addc_u32 s99, s19, s5
	s_lshl_b64 s[18:19], s[10:11], 9
	s_add_u32 s100, s15, s16
	s_addc_u32 s101, s20, s17
	s_add_u32 s100, s100, s18
	s_addc_u32 s101, s101, s19
	v_lshlrev_b32_e32 v237, 1, v182
	v_lshlrev_b32_e32 v238, 1, v180
	v_mov_b32_e32 v100, v237
	v_add_u32_e32 v104, 0x8000, v237
	v_add_u32_e32 v108, 0x10000, v237
	v_add_u32_e32 v112, 0x18000, v237
	global_load_dwordx4 v[100:103], v100, s[98:99]
	global_load_dwordx4 v[104:107], v104, s[98:99]
	global_load_dwordx4 v[108:111], v108, s[98:99]
	global_load_dwordx4 v[112:115], v112, s[98:99]
	v_add_u32_e32 v240, 0x20000, v237
	v_add_u32_e32 v244, 0x28000, v237
	v_add_u32_e32 v248, 0x30000, v237
	v_add_u32_e32 v252, 0x38000, v237
	global_load_dwordx4 v[240:243], v240, s[98:99]
	global_load_dwordx4 v[244:247], v244, s[98:99]
	global_load_dwordx4 v[248:251], v248, s[98:99]
	global_load_dwordx4 v[252:255], v252, s[98:99]
	s_barrier
	s_waitcnt vmcnt(7)
	ds_write_b128 v202, v[100:103]
	s_waitcnt vmcnt(6)
	ds_write_b128 v202, v[104:107] offset:8448
	s_waitcnt vmcnt(5)
	ds_write_b128 v202, v[108:111] offset:16896
	s_waitcnt vmcnt(4)
	ds_write_b128 v202, v[112:115] offset:25344
	v_add_u32_e32 v100, 0x40000, v237
	v_add_u32_e32 v104, 0x48000, v237
	v_add_u32_e32 v108, 0x50000, v237
	v_add_u32_e32 v112, 0x58000, v237
	s_waitcnt lgkmcnt(0)
	s_barrier
	global_load_dwordx4 v[100:103], v100, s[98:99]
	global_load_dwordx4 v[104:107], v104, s[98:99]
	global_load_dwordx4 v[108:111], v108, s[98:99]
	global_load_dwordx4 v[112:115], v112, s[98:99]
	s_and_b64 vcc, exec, s[12:13]
	s_cbranch_vccz .LBB0_1094
	ds_read_b128 v[48:51], v193
	ds_read_b128 v[64:67], v193 offset:64
	ds_read_b128 v[80:83], v193 offset:8448
	ds_read_b128 v[96:99], v193 offset:8512
	ds_read_b128 v[116:119], v193 offset:128
	ds_read_b128 v[120:123], v193 offset:25472
	s_waitcnt lgkmcnt(5)
	v_mfma_f32_16x16x32_bf16 v[48:51], v[48:51], v[32:35], 0
	s_waitcnt lgkmcnt(4)
	v_mfma_f32_16x16x32_bf16 v[48:51], v[64:67], v[28:31], v[48:51]
	ds_read_b128 v[64:67], v193 offset:192
	s_waitcnt lgkmcnt(2)
	v_mfma_f32_16x16x32_bf16 v[48:51], v[116:119], v[24:27], v[48:51]
	ds_read_b128 v[116:119], v193 offset:256
	v_mfma_f32_16x16x32_bf16 v[80:83], v[80:83], v[32:35], 0
	s_waitcnt lgkmcnt(1)
	v_mfma_f32_16x16x32_bf16 v[48:51], v[64:67], v[20:23], v[48:51]
	ds_read_b128 v[64:67], v193 offset:320
	s_waitcnt lgkmcnt(1)
	v_mfma_f32_16x16x32_bf16 v[48:51], v[116:119], v[16:19], v[48:51]
	ds_read_b128 v[116:119], v193 offset:384
	s_waitcnt lgkmcnt(1)
	v_mfma_f32_16x16x32_bf16 v[48:51], v[64:67], v[12:15], v[48:51]
	ds_read_b128 v[64:67], v193 offset:448
	s_waitcnt lgkmcnt(1)
	v_mfma_f32_16x16x32_bf16 v[48:51], v[116:119], v[8:11], v[48:51]
	ds_read_b128 v[116:119], v193 offset:17024
	s_waitcnt lgkmcnt(1)
	v_mfma_f32_16x16x32_bf16 v[48:51], v[64:67], v[4:7], v[48:51]
	ds_read_b128 v[64:67], v193 offset:8576
	v_mfma_f32_16x16x32_bf16 v[80:83], v[96:99], v[28:31], v[80:83]
	ds_read_b128 v[96:99], v193 offset:8640
	s_waitcnt lgkmcnt(1)
	v_mfma_f32_16x16x32_bf16 v[64:67], v[64:67], v[24:27], v[80:83]
	s_nop 4
	ds_read_b128 v[80:83], v193 offset:8704
	s_waitcnt lgkmcnt(1)
	v_mfma_f32_16x16x32_bf16 v[64:67], v[96:99], v[20:23], v[64:67]
	ds_read_b128 v[96:99], v193 offset:8768
	s_waitcnt lgkmcnt(1)
	v_mfma_f32_16x16x32_bf16 v[64:67], v[80:83], v[16:19], v[64:67]
	ds_read_b128 v[80:83], v193 offset:8832
	s_waitcnt lgkmcnt(1)
	v_mfma_f32_16x16x32_bf16 v[64:67], v[96:99], v[12:15], v[64:67]
	ds_read_b128 v[96:99], v193 offset:8896
	s_waitcnt lgkmcnt(1)
	v_mfma_f32_16x16x32_bf16 v[64:67], v[80:83], v[8:11], v[64:67]
	ds_read_b128 v[80:83], v193 offset:16896
	s_waitcnt lgkmcnt(1)
	v_mfma_f32_16x16x32_bf16 v[64:67], v[96:99], v[4:7], v[64:67]
	ds_read_b128 v[96:99], v193 offset:16960
	s_waitcnt lgkmcnt(1)
	v_mfma_f32_16x16x32_bf16 v[80:83], v[80:83], v[32:35], 0
	s_waitcnt lgkmcnt(0)
	v_mfma_f32_16x16x32_bf16 v[80:83], v[96:99], v[28:31], v[80:83]
	ds_read_b128 v[96:99], v193 offset:17088
	v_mfma_f32_16x16x32_bf16 v[80:83], v[116:119], v[24:27], v[80:83]
	ds_read_b128 v[116:119], v193 offset:17152
	s_waitcnt lgkmcnt(1)
	v_mfma_f32_16x16x32_bf16 v[80:83], v[96:99], v[20:23], v[80:83]
	ds_read_b128 v[96:99], v193 offset:17216
	s_waitcnt lgkmcnt(1)
	v_mfma_f32_16x16x32_bf16 v[80:83], v[116:119], v[16:19], v[80:83]
	ds_read_b128 v[116:119], v193 offset:17280
	s_waitcnt lgkmcnt(1)
	v_mfma_f32_16x16x32_bf16 v[80:83], v[96:99], v[12:15], v[80:83]
	ds_read_b128 v[96:99], v193 offset:17344
	s_waitcnt lgkmcnt(1)
	v_mfma_f32_16x16x32_bf16 v[80:83], v[116:119], v[8:11], v[80:83]
	ds_read_b128 v[116:119], v193 offset:25344
	s_waitcnt lgkmcnt(1)
	v_mfma_f32_16x16x32_bf16 v[80:83], v[96:99], v[4:7], v[80:83]
	ds_read_b128 v[96:99], v193 offset:25408
	s_waitcnt lgkmcnt(1)
	v_mfma_f32_16x16x32_bf16 v[116:119], v[116:119], v[32:35], 0
	s_waitcnt lgkmcnt(0)
	v_mfma_f32_16x16x32_bf16 v[96:99], v[96:99], v[28:31], v[116:119]
	s_nop 5
	ds_read_b128 v[116:119], v193 offset:25536
	v_mfma_f32_16x16x32_bf16 v[96:99], v[120:123], v[24:27], v[96:99]
	ds_read_b128 v[120:123], v193 offset:25600
	s_waitcnt lgkmcnt(1)
	v_mfma_f32_16x16x32_bf16 v[96:99], v[116:119], v[20:23], v[96:99]
	ds_read_b128 v[116:119], v193 offset:25664
	s_waitcnt lgkmcnt(1)
	v_mfma_f32_16x16x32_bf16 v[96:99], v[120:123], v[16:19], v[96:99]
	ds_read_b128 v[120:123], v193 offset:25728
	s_waitcnt lgkmcnt(1)
	v_mfma_f32_16x16x32_bf16 v[96:99], v[116:119], v[12:15], v[96:99]
	ds_read_b128 v[116:119], v193 offset:25792
	s_waitcnt lgkmcnt(1)
	v_mfma_f32_16x16x32_bf16 v[96:99], v[120:123], v[8:11], v[96:99]
	s_waitcnt lgkmcnt(0)
	v_mfma_f32_16x16x32_bf16 v[96:99], v[116:119], v[4:7], v[96:99]
; #define LAS __attribute__((address_space(3)))
; #define LOADK(i) do { _Pragma("unroll") for (int j = 0; j < 4; ++j) st[j] = *(const u32x4*)(kbase + ((i) * 64 + j * 16) * 1024 + koff); } while (0)
; #define LOADV(i) do { _Pragma("unroll") for (int j = 0; j < 4; ++j) st[j] = *(const u32x4*)(vbase + (j * 64 * 256 + (i) * 64) + voff); } while (0)
; #define STOREK() do { _Pragma("unroll") for (int j = 0; j < 4; ++j) *(LAS u32x4*)(kst + j * 16 * 528) = st[j]; } while (0)
; __device__ __forceinline__ void ph_attn(const Params& p, LAS unsigned char* lds) {
;     ...
;         const bf16_t* kbase = kb + (size_t)kvb * 256 * 1024 + h * 256; const bf16_t* vbase = vt + ((size_t)kvb * 1024 + h * 256) * 256;
;     ...
;         f32x4 sc[16];
;         LOADK(0);
; #pragma unroll
;         for (int i = 0; i < 4; ++i) {
;             __syncthreads(); STOREK(); __syncthreads();
;             if (i < 3) LOADK(i + 1); else LOADV(0);
;             if (active) {
; #pragma unroll
;                 for (int sub = 0; sub < 4; ++sub) {
;                     f32x4 a = {0.f, 0.f, 0.f, 0.f};
; #pragma unroll
;                     for (int ks = 0; ks < 8; ++ks) {
;                         const bf16x8 kf = *(const LAS bf16x8*)(krd + sub * 16 * 528 + ks * 64);
;                         a = __builtin_amdgcn_mfma_f32_16x16x32_bf16(kf, qf[ks], a, 0, 0, 0);
;                     }
;                     sc[i * 4 + sub] = a;
;                 }
;             }
;         }
.LBB0_1094:
	s_barrier
	s_waitcnt vmcnt(7)
	ds_write_b128 v202, v[240:243]
	s_waitcnt vmcnt(6)
	ds_write_b128 v202, v[244:247] offset:8448
	s_waitcnt vmcnt(5)
	ds_write_b128 v202, v[248:251] offset:16896
	s_waitcnt vmcnt(4)
	ds_write_b128 v202, v[252:255] offset:25344
	v_add_u32_e32 v240, 0x60000, v237
	v_add_u32_e32 v244, 0x68000, v237
	v_add_u32_e32 v248, 0x70000, v237
	v_add_u32_e32 v252, 0x78000, v237
	s_waitcnt lgkmcnt(0)
	s_barrier
	global_load_dwordx4 v[240:243], v240, s[98:99]
	global_load_dwordx4 v[244:247], v244, s[98:99]
	global_load_dwordx4 v[248:251], v248, s[98:99]
	global_load_dwordx4 v[252:255], v252, s[98:99]
	v_cndmask_b32_e64 v1, 0, 1, s[12:13]
	v_cmp_ne_u32_e64 s[4:5], 1, v1
	s_andn2_b64 vcc, exec, s[12:13]
	s_cbranch_vccnz .LBB0_1096
	ds_read_b128 v[44:47], v193
	ds_read_b128 v[60:63], v193 offset:64
	ds_read_b128 v[76:79], v193 offset:8448
	ds_read_b128 v[92:95], v193 offset:8512
	ds_read_b128 v[116:119], v193 offset:128
	ds_read_b128 v[120:123], v193 offset:25472
	s_waitcnt lgkmcnt(5)
	v_mfma_f32_16x16x32_bf16 v[44:47], v[44:47], v[32:35], 0
	s_waitcnt lgkmcnt(4)
	v_mfma_f32_16x16x32_bf16 v[44:47], v[60:63], v[28:31], v[44:47]
	ds_read_b128 v[60:63], v193 offset:192
	s_waitcnt lgkmcnt(2)
	v_mfma_f32_16x16x32_bf16 v[44:47], v[116:119], v[24:27], v[44:47]
	ds_read_b128 v[116:119], v193 offset:256
	v_mfma_f32_16x16x32_bf16 v[76:79], v[76:79], v[32:35], 0
	s_waitcnt lgkmcnt(1)
	v_mfma_f32_16x16x32_bf16 v[44:47], v[60:63], v[20:23], v[44:47]
	ds_read_b128 v[60:63], v193 offset:320
	s_waitcnt lgkmcnt(1)
	v_mfma_f32_16x16x32_bf16 v[44:47], v[116:119], v[16:19], v[44:47]
	ds_read_b128 v[116:119], v193 offset:384
	s_waitcnt lgkmcnt(1)
	v_mfma_f32_16x16x32_bf16 v[44:47], v[60:63], v[12:15], v[44:47]
	ds_read_b128 v[60:63], v193 offset:448
	s_waitcnt lgkmcnt(1)
	v_mfma_f32_16x16x32_bf16 v[44:47], v[116:119], v[8:11], v[44:47]
	ds_read_b128 v[116:119], v193 offset:17024
	s_waitcnt lgkmcnt(1)
	v_mfma_f32_16x16x32_bf16 v[44:47], v[60:63], v[4:7], v[44:47]
	ds_read_b128 v[60:63], v193 offset:8576
	v_mfma_f32_16x16x32_bf16 v[76:79], v[92:95], v[28:31], v[76:79]
	ds_read_b128 v[92:95], v193 offset:8640
	s_waitcnt lgkmcnt(1)
	v_mfma_f32_16x16x32_bf16 v[60:63], v[60:63], v[24:27], v[76:79]
	s_nop 4
	ds_read_b128 v[76:79], v193 offset:8704
	s_waitcnt lgkmcnt(1)
	v_mfma_f32_16x16x32_bf16 v[60:63], v[92:95], v[20:23], v[60:63]
	ds_read_b128 v[92:95], v193 offset:8768
	s_waitcnt lgkmcnt(1)
	v_mfma_f32_16x16x32_bf16 v[60:63], v[76:79], v[16:19], v[60:63]
	ds_read_b128 v[76:79], v193 offset:8832
	s_waitcnt lgkmcnt(1)
	v_mfma_f32_16x16x32_bf16 v[60:63], v[92:95], v[12:15], v[60:63]
	ds_read_b128 v[92:95], v193 offset:8896
	s_waitcnt lgkmcnt(1)
	v_mfma_f32_16x16x32_bf16 v[60:63], v[76:79], v[8:11], v[60:63]
	ds_read_b128 v[76:79], v193 offset:16896
	s_waitcnt lgkmcnt(1)
	v_mfma_f32_16x16x32_bf16 v[60:63], v[92:95], v[4:7], v[60:63]
	ds_read_b128 v[92:95], v193 offset:16960
	s_waitcnt lgkmcnt(1)
	v_mfma_f32_16x16x32_bf16 v[76:79], v[76:79], v[32:35], 0
	s_waitcnt lgkmcnt(0)
	v_mfma_f32_16x16x32_bf16 v[76:79], v[92:95], v[28:31], v[76:79]
	ds_read_b128 v[92:95], v193 offset:17088
	v_mfma_f32_16x16x32_bf16 v[76:79], v[116:119], v[24:27], v[76:79]
	ds_read_b128 v[116:119], v193 offset:17152
	s_waitcnt lgkmcnt(1)
	v_mfma_f32_16x16x32_bf16 v[76:79], v[92:95], v[20:23], v[76:79]
	ds_read_b128 v[92:95], v193 offset:17216
	s_waitcnt lgkmcnt(1)
	v_mfma_f32_16x16x32_bf16 v[76:79], v[116:119], v[16:19], v[76:79]
	ds_read_b128 v[116:119], v193 offset:17280
	s_waitcnt lgkmcnt(1)
	v_mfma_f32_16x16x32_bf16 v[76:79], v[92:95], v[12:15], v[76:79]
	ds_read_b128 v[92:95], v193 offset:17344
	s_waitcnt lgkmcnt(1)
	v_mfma_f32_16x16x32_bf16 v[76:79], v[116:119], v[8:11], v[76:79]
	ds_read_b128 v[116:119], v193 offset:25344
	s_waitcnt lgkmcnt(1)
	v_mfma_f32_16x16x32_bf16 v[76:79], v[92:95], v[4:7], v[76:79]
	ds_read_b128 v[92:95], v193 offset:25408
	s_waitcnt lgkmcnt(1)
	v_mfma_f32_16x16x32_bf16 v[116:119], v[116:119], v[32:35], 0
	s_waitcnt lgkmcnt(0)
	v_mfma_f32_16x16x32_bf16 v[92:95], v[92:95], v[28:31], v[116:119]
	s_nop 5
	ds_read_b128 v[116:119], v193 offset:25536
	v_mfma_f32_16x16x32_bf16 v[92:95], v[120:123], v[24:27], v[92:95]
	ds_read_b128 v[120:123], v193 offset:25600
	s_waitcnt lgkmcnt(1)
	v_mfma_f32_16x16x32_bf16 v[92:95], v[116:119], v[20:23], v[92:95]
	ds_read_b128 v[116:119], v193 offset:25664
	s_waitcnt lgkmcnt(1)
	v_mfma_f32_16x16x32_bf16 v[92:95], v[120:123], v[16:19], v[92:95]
	ds_read_b128 v[120:123], v193 offset:25728
	s_waitcnt lgkmcnt(1)
	v_mfma_f32_16x16x32_bf16 v[92:95], v[116:119], v[12:15], v[92:95]
	ds_read_b128 v[116:119], v193 offset:25792
	s_waitcnt lgkmcnt(1)
	v_mfma_f32_16x16x32_bf16 v[92:95], v[120:123], v[8:11], v[92:95]
	s_waitcnt lgkmcnt(0)
	v_mfma_f32_16x16x32_bf16 v[92:95], v[116:119], v[4:7], v[92:95]
; #define LAS __attribute__((address_space(3)))
; #define LOADK(i) do { _Pragma("unroll") for (int j = 0; j < 4; ++j) st[j] = *(const u32x4*)(kbase + ((i) * 64 + j * 16) * 1024 + koff); } while (0)
; #define LOADV(i) do { _Pragma("unroll") for (int j = 0; j < 4; ++j) st[j] = *(const u32x4*)(vbase + (j * 64 * 256 + (i) * 64) + voff); } while (0)
; #define STOREK() do { _Pragma("unroll") for (int j = 0; j < 4; ++j) *(LAS u32x4*)(kst + j * 16 * 528) = st[j]; } while (0)
; __device__ __forceinline__ void ph_attn(const Params& p, LAS unsigned char* lds) {
;     ...
;         const bf16_t* kbase = kb + (size_t)kvb * 256 * 1024 + h * 256; const bf16_t* vbase = vt + ((size_t)kvb * 1024 + h * 256) * 256;
;     ...
;         f32x4 sc[16];
;         LOADK(0);
; #pragma unroll
;         for (int i = 0; i < 4; ++i) {
;             __syncthreads(); STOREK(); __syncthreads();
;             if (i < 3) LOADK(i + 1); else LOADV(0);
;             if (active) {
; #pragma unroll
;                 for (int sub = 0; sub < 4; ++sub) {
;                     f32x4 a = {0.f, 0.f, 0.f, 0.f};
; #pragma unroll
;                     for (int ks = 0; ks < 8; ++ks) {
;                         const bf16x8 kf = *(const LAS bf16x8*)(krd + sub * 16 * 528 + ks * 64);
;                         a = __builtin_amdgcn_mfma_f32_16x16x32_bf16(kf, qf[ks], a, 0, 0, 0);
;                     }
;                     sc[i * 4 + sub] = a;
;                 }
;             }
;         }
.LBB0_1096:
	s_barrier
	s_waitcnt vmcnt(7)
	ds_write_b128 v202, v[100:103]
	s_waitcnt vmcnt(6)
	ds_write_b128 v202, v[104:107] offset:8448
	s_waitcnt vmcnt(5)
	ds_write_b128 v202, v[108:111] offset:16896
	s_waitcnt vmcnt(4)
	ds_write_b128 v202, v[112:115] offset:25344
	v_mov_b32_e32 v100, v238
	v_add_u32_e32 v104, 0x8000, v238
	v_add_u32_e32 v108, 0x10000, v238
	v_add_u32_e32 v112, 0x18000, v238
	s_waitcnt lgkmcnt(0)
	s_barrier
	global_load_dwordx4 v[100:103], v100, s[100:101]
	global_load_dwordx4 v[104:107], v104, s[100:101]
	global_load_dwordx4 v[108:111], v108, s[100:101]
	global_load_dwordx4 v[112:115], v112, s[100:101]
	s_and_b64 vcc, exec, s[4:5]
	s_cbranch_vccnz .LBB0_1098
	ds_read_b128 v[40:43], v193
	ds_read_b128 v[56:59], v193 offset:64
	ds_read_b128 v[72:75], v193 offset:8448
	ds_read_b128 v[88:91], v193 offset:8512
	ds_read_b128 v[116:119], v193 offset:128
	ds_read_b128 v[120:123], v193 offset:25472
	s_waitcnt lgkmcnt(5)
	v_mfma_f32_16x16x32_bf16 v[40:43], v[40:43], v[32:35], 0
	s_waitcnt lgkmcnt(4)
	v_mfma_f32_16x16x32_bf16 v[40:43], v[56:59], v[28:31], v[40:43]
	ds_read_b128 v[56:59], v193 offset:192
	s_waitcnt lgkmcnt(2)
	v_mfma_f32_16x16x32_bf16 v[40:43], v[116:119], v[24:27], v[40:43]
	ds_read_b128 v[116:119], v193 offset:256
	v_mfma_f32_16x16x32_bf16 v[72:75], v[72:75], v[32:35], 0
	s_waitcnt lgkmcnt(1)
	v_mfma_f32_16x16x32_bf16 v[40:43], v[56:59], v[20:23], v[40:43]
	ds_read_b128 v[56:59], v193 offset:320
	s_waitcnt lgkmcnt(1)
	v_mfma_f32_16x16x32_bf16 v[40:43], v[116:119], v[16:19], v[40:43]
	ds_read_b128 v[116:119], v193 offset:384
	s_waitcnt lgkmcnt(1)
	v_mfma_f32_16x16x32_bf16 v[40:43], v[56:59], v[12:15], v[40:43]
	ds_read_b128 v[56:59], v193 offset:448
	s_waitcnt lgkmcnt(1)
	v_mfma_f32_16x16x32_bf16 v[40:43], v[116:119], v[8:11], v[40:43]
	ds_read_b128 v[116:119], v193 offset:17024
	s_waitcnt lgkmcnt(1)
	v_mfma_f32_16x16x32_bf16 v[40:43], v[56:59], v[4:7], v[40:43]
	ds_read_b128 v[56:59], v193 offset:8576
	v_mfma_f32_16x16x32_bf16 v[72:75], v[88:91], v[28:31], v[72:75]
	ds_read_b128 v[88:91], v193 offset:8640
	s_waitcnt lgkmcnt(1)
	v_mfma_f32_16x16x32_bf16 v[56:59], v[56:59], v[24:27], v[72:75]
	s_nop 4
	ds_read_b128 v[72:75], v193 offset:8704
	s_waitcnt lgkmcnt(1)
	v_mfma_f32_16x16x32_bf16 v[56:59], v[88:91], v[20:23], v[56:59]
	ds_read_b128 v[88:91], v193 offset:8768
	s_waitcnt lgkmcnt(1)
	v_mfma_f32_16x16x32_bf16 v[56:59], v[72:75], v[16:19], v[56:59]
	ds_read_b128 v[72:75], v193 offset:8832
	s_waitcnt lgkmcnt(1)
	v_mfma_f32_16x16x32_bf16 v[56:59], v[88:91], v[12:15], v[56:59]
	ds_read_b128 v[88:91], v193 offset:8896
	s_waitcnt lgkmcnt(1)
	v_mfma_f32_16x16x32_bf16 v[56:59], v[72:75], v[8:11], v[56:59]
	ds_read_b128 v[72:75], v193 offset:16896
	s_waitcnt lgkmcnt(1)
	v_mfma_f32_16x16x32_bf16 v[56:59], v[88:91], v[4:7], v[56:59]
	ds_read_b128 v[88:91], v193 offset:16960
	s_waitcnt lgkmcnt(1)
	v_mfma_f32_16x16x32_bf16 v[72:75], v[72:75], v[32:35], 0
	s_waitcnt lgkmcnt(0)
	v_mfma_f32_16x16x32_bf16 v[72:75], v[88:91], v[28:31], v[72:75]
	ds_read_b128 v[88:91], v193 offset:17088
	v_mfma_f32_16x16x32_bf16 v[72:75], v[116:119], v[24:27], v[72:75]
	ds_read_b128 v[116:119], v193 offset:17152
	s_waitcnt lgkmcnt(1)
	v_mfma_f32_16x16x32_bf16 v[72:75], v[88:91], v[20:23], v[72:75]
	ds_read_b128 v[88:91], v193 offset:17216
	s_waitcnt lgkmcnt(1)
	v_mfma_f32_16x16x32_bf16 v[72:75], v[116:119], v[16:19], v[72:75]
	ds_read_b128 v[116:119], v193 offset:17280
	s_waitcnt lgkmcnt(1)
	v_mfma_f32_16x16x32_bf16 v[72:75], v[88:91], v[12:15], v[72:75]
	ds_read_b128 v[88:91], v193 offset:17344
	s_waitcnt lgkmcnt(1)
	v_mfma_f32_16x16x32_bf16 v[72:75], v[116:119], v[8:11], v[72:75]
	ds_read_b128 v[116:119], v193 offset:25344
	s_waitcnt lgkmcnt(1)
	v_mfma_f32_16x16x32_bf16 v[72:75], v[88:91], v[4:7], v[72:75]
	ds_read_b128 v[88:91], v193 offset:25408
	s_waitcnt lgkmcnt(1)
	v_mfma_f32_16x16x32_bf16 v[116:119], v[116:119], v[32:35], 0
	s_waitcnt lgkmcnt(0)
	v_mfma_f32_16x16x32_bf16 v[88:91], v[88:91], v[28:31], v[116:119]
	s_nop 5
	ds_read_b128 v[116:119], v193 offset:25536
	v_mfma_f32_16x16x32_bf16 v[88:91], v[120:123], v[24:27], v[88:91]
	ds_read_b128 v[120:123], v193 offset:25600
	s_waitcnt lgkmcnt(1)
	v_mfma_f32_16x16x32_bf16 v[88:91], v[116:119], v[20:23], v[88:91]
	ds_read_b128 v[116:119], v193 offset:25664
	s_waitcnt lgkmcnt(1)
	v_mfma_f32_16x16x32_bf16 v[88:91], v[120:123], v[16:19], v[88:91]
	ds_read_b128 v[120:123], v193 offset:25728
	s_waitcnt lgkmcnt(1)
	v_mfma_f32_16x16x32_bf16 v[88:91], v[116:119], v[12:15], v[88:91]
	ds_read_b128 v[116:119], v193 offset:25792
	s_waitcnt lgkmcnt(1)
	v_mfma_f32_16x16x32_bf16 v[88:91], v[120:123], v[8:11], v[88:91]
	s_waitcnt lgkmcnt(0)
	v_mfma_f32_16x16x32_bf16 v[88:91], v[116:119], v[4:7], v[88:91]
; #define LAS __attribute__((address_space(3)))
; #define LOADK(i) do { _Pragma("unroll") for (int j = 0; j < 4; ++j) st[j] = *(const u32x4*)(kbase + ((i) * 64 + j * 16) * 1024 + koff); } while (0)
; #define LOADV(i) do { _Pragma("unroll") for (int j = 0; j < 4; ++j) st[j] = *(const u32x4*)(vbase + (j * 64 * 256 + (i) * 64) + voff); } while (0)
; #define STOREK() do { _Pragma("unroll") for (int j = 0; j < 4; ++j) *(LAS u32x4*)(kst + j * 16 * 528) = st[j]; } while (0)
; __device__ __forceinline__ void ph_attn(const Params& p, LAS unsigned char* lds) {
;     ...
;         const bf16_t* kbase = kb + (size_t)kvb * 256 * 1024 + h * 256; const bf16_t* vbase = vt + ((size_t)kvb * 1024 + h * 256) * 256;
;     ...
;         f32x4 sc[16];
;         LOADK(0);
; #pragma unroll
;         for (int i = 0; i < 4; ++i) {
;             __syncthreads(); STOREK(); __syncthreads();
;             if (i < 3) LOADK(i + 1); else LOADV(0);
;             if (active) {
; #pragma unroll
;                 for (int sub = 0; sub < 4; ++sub) {
;                     f32x4 a = {0.f, 0.f, 0.f, 0.f};
; #pragma unroll
;                     for (int ks = 0; ks < 8; ++ks) {
;                         const bf16x8 kf = *(const LAS bf16x8*)(krd + sub * 16 * 528 + ks * 64);
;                         a = __builtin_amdgcn_mfma_f32_16x16x32_bf16(kf, qf[ks], a, 0, 0, 0);
;                     }
;                     sc[i * 4 + sub] = a;
;                 }
;             }
;         }
.LBB0_1098:
	s_lshl_b64 s[18:19], s[10:11], 9
	s_add_u32 s28, s15, s16
	s_addc_u32 s29, s20, s17
	s_add_u32 s28, s28, s18
	s_addc_u32 s29, s29, s19
	s_barrier
	s_waitcnt vmcnt(7)
	ds_write_b128 v202, v[240:243]
	s_waitcnt vmcnt(6)
	ds_write_b128 v202, v[244:247] offset:8448
	s_waitcnt vmcnt(5)
	ds_write_b128 v202, v[248:251] offset:16896
	s_waitcnt vmcnt(4)
	ds_write_b128 v202, v[252:255] offset:25344
	v_mov_b32_e32 v240, v238
	v_add_u32_e32 v244, 0x8000, v238
	v_add_u32_e32 v248, 0x10000, v238
	v_add_u32_e32 v252, 0x18000, v238
	s_waitcnt lgkmcnt(0)
	s_barrier
	global_load_dwordx4 v[240:243], v240, s[100:101] offset:128
	global_load_dwordx4 v[244:247], v244, s[100:101] offset:128
	global_load_dwordx4 v[248:251], v248, s[100:101] offset:128
	global_load_dwordx4 v[252:255], v252, s[100:101] offset:128
	s_and_b64 vcc, exec, s[4:5]
	s_cbranch_vccnz .LBB0_1100
	ds_read_b128 v[36:39], v193
	ds_read_b128 v[52:55], v193 offset:64
	ds_read_b128 v[68:71], v193 offset:8448
	ds_read_b128 v[84:87], v193 offset:8512
	ds_read_b128 v[116:119], v193 offset:128
	ds_read_b128 v[120:123], v193 offset:25472
	s_waitcnt lgkmcnt(5)
	v_mfma_f32_16x16x32_bf16 v[36:39], v[36:39], v[32:35], 0
	s_waitcnt lgkmcnt(4)
	v_mfma_f32_16x16x32_bf16 v[36:39], v[52:55], v[28:31], v[36:39]
	ds_read_b128 v[52:55], v193 offset:192
	s_waitcnt lgkmcnt(2)
	v_mfma_f32_16x16x32_bf16 v[36:39], v[116:119], v[24:27], v[36:39]
	ds_read_b128 v[116:119], v193 offset:256
	v_mfma_f32_16x16x32_bf16 v[68:71], v[68:71], v[32:35], 0
	s_waitcnt lgkmcnt(1)
	v_mfma_f32_16x16x32_bf16 v[36:39], v[52:55], v[20:23], v[36:39]
	ds_read_b128 v[52:55], v193 offset:320
	s_waitcnt lgkmcnt(1)
	v_mfma_f32_16x16x32_bf16 v[36:39], v[116:119], v[16:19], v[36:39]
	ds_read_b128 v[116:119], v193 offset:384
	s_waitcnt lgkmcnt(1)
	v_mfma_f32_16x16x32_bf16 v[36:39], v[52:55], v[12:15], v[36:39]
	ds_read_b128 v[52:55], v193 offset:448
	s_waitcnt lgkmcnt(1)
	v_mfma_f32_16x16x32_bf16 v[36:39], v[116:119], v[8:11], v[36:39]
	ds_read_b128 v[116:119], v193 offset:17024
	s_waitcnt lgkmcnt(1)
	v_mfma_f32_16x16x32_bf16 v[36:39], v[52:55], v[4:7], v[36:39]
	ds_read_b128 v[52:55], v193 offset:8576
	v_mfma_f32_16x16x32_bf16 v[68:71], v[84:87], v[28:31], v[68:71]
	ds_read_b128 v[84:87], v193 offset:8640
	s_waitcnt lgkmcnt(1)
	v_mfma_f32_16x16x32_bf16 v[52:55], v[52:55], v[24:27], v[68:71]
	s_nop 4
	ds_read_b128 v[68:71], v193 offset:8704
	s_waitcnt lgkmcnt(1)
	v_mfma_f32_16x16x32_bf16 v[52:55], v[84:87], v[20:23], v[52:55]
	ds_read_b128 v[84:87], v193 offset:8768
	s_waitcnt lgkmcnt(1)
	v_mfma_f32_16x16x32_bf16 v[52:55], v[68:71], v[16:19], v[52:55]
	ds_read_b128 v[68:71], v193 offset:8832
	s_waitcnt lgkmcnt(1)
	v_mfma_f32_16x16x32_bf16 v[52:55], v[84:87], v[12:15], v[52:55]
	ds_read_b128 v[84:87], v193 offset:8896
	s_waitcnt lgkmcnt(1)
	v_mfma_f32_16x16x32_bf16 v[52:55], v[68:71], v[8:11], v[52:55]
	ds_read_b128 v[68:71], v193 offset:16896
	s_waitcnt lgkmcnt(1)
	v_mfma_f32_16x16x32_bf16 v[52:55], v[84:87], v[4:7], v[52:55]
	ds_read_b128 v[84:87], v193 offset:16960
	s_waitcnt lgkmcnt(1)
	v_mfma_f32_16x16x32_bf16 v[68:71], v[68:71], v[32:35], 0
	s_waitcnt lgkmcnt(0)
	v_mfma_f32_16x16x32_bf16 v[68:71], v[84:87], v[28:31], v[68:71]
	ds_read_b128 v[84:87], v193 offset:17088
	v_mfma_f32_16x16x32_bf16 v[68:71], v[116:119], v[24:27], v[68:71]
	ds_read_b128 v[116:119], v193 offset:17152
	s_waitcnt lgkmcnt(1)
	v_mfma_f32_16x16x32_bf16 v[68:71], v[84:87], v[20:23], v[68:71]
	ds_read_b128 v[84:87], v193 offset:17216
	s_waitcnt lgkmcnt(1)
	v_mfma_f32_16x16x32_bf16 v[68:71], v[116:119], v[16:19], v[68:71]
	ds_read_b128 v[116:119], v193 offset:17280
	s_waitcnt lgkmcnt(1)
	v_mfma_f32_16x16x32_bf16 v[68:71], v[84:87], v[12:15], v[68:71]
	ds_read_b128 v[84:87], v193 offset:17344
	s_waitcnt lgkmcnt(1)
	v_mfma_f32_16x16x32_bf16 v[68:71], v[116:119], v[8:11], v[68:71]
	ds_read_b128 v[116:119], v193 offset:25344
	s_waitcnt lgkmcnt(1)
	v_mfma_f32_16x16x32_bf16 v[68:71], v[84:87], v[4:7], v[68:71]
	ds_read_b128 v[84:87], v193 offset:25408
	s_waitcnt lgkmcnt(1)
	v_mfma_f32_16x16x32_bf16 v[116:119], v[116:119], v[32:35], 0
	s_waitcnt lgkmcnt(0)
	v_mfma_f32_16x16x32_bf16 v[84:87], v[84:87], v[28:31], v[116:119]
	s_nop 5
	ds_read_b128 v[116:119], v193 offset:25536
	v_mfma_f32_16x16x32_bf16 v[84:87], v[120:123], v[24:27], v[84:87]
	ds_read_b128 v[120:123], v193 offset:25600
	s_waitcnt lgkmcnt(1)
	v_mfma_f32_16x16x32_bf16 v[84:87], v[116:119], v[20:23], v[84:87]
	ds_read_b128 v[116:119], v193 offset:25664
	s_waitcnt lgkmcnt(1)
	v_mfma_f32_16x16x32_bf16 v[84:87], v[120:123], v[16:19], v[84:87]
	ds_read_b128 v[120:123], v193 offset:25728
	s_waitcnt lgkmcnt(1)
	v_mfma_f32_16x16x32_bf16 v[84:87], v[116:119], v[12:15], v[84:87]
	ds_read_b128 v[116:119], v193 offset:25792
	s_waitcnt lgkmcnt(1)
	v_mfma_f32_16x16x32_bf16 v[84:87], v[120:123], v[8:11], v[84:87]
	s_waitcnt lgkmcnt(0)
	v_mfma_f32_16x16x32_bf16 v[84:87], v[116:119], v[4:7], v[84:87]

; #define LAS __attribute__((address_space(3)))
; #define LOADV(i) do { _Pragma("unroll") for (int j = 0; j < 4; ++j) st[j] = *(const u32x4*)(vbase + (j * 64 * 256 + (i) * 64) + voff); } while (0)
; #define STOREV() do { _Pragma("unroll") for (int j = 0; j < 4; ++j) *(LAS u32x4*)(vst + j * 64 * 144) = st[j]; } while (0)
; __device__ __forceinline__ void ph_attn(const Params& p, LAS unsigned char* lds) {
;     ...
; #pragma unroll 1
;         for (int i = 0; i < 4; ++i) {
;             __syncthreads(); STOREV(); __syncthreads();
;             if (i < 3) LOADV(i + 1);
;             if (active) {
; #pragma unroll
;                 for (int ks = 0; ks < 2; ++ks) {
;                     const bf16x8 pf = *(const LAS bf16x8*)(pw + fq * 8 + i * 128 + ks * 64);
; #pragma unroll
;                     for (int dt = 0; dt < 16; ++dt) {
;                         const bf16x8 vf = *(const LAS bf16x8*)(vrd + dt * 16 * 144 + ks * 64);
;                         oa[dt] = __builtin_amdgcn_mfma_f32_16x16x32_bf16(vf, pf, oa[dt], 0, 0, 0);
;                     }
;                 }
;             }
;         }
.LBB0_1104:
	s_waitcnt lgkmcnt(0)
	s_barrier
	s_waitcnt vmcnt(7)
	ds_write_b128 v199, v[100:103]
	s_waitcnt vmcnt(6)
	ds_write_b128 v199, v[104:107] offset:9216
	s_waitcnt vmcnt(5)
	ds_write_b128 v199, v[108:111] offset:18432
	s_waitcnt vmcnt(4)
	ds_write_b128 v199, v[112:115] offset:27648
	v_mov_b32_e32 v100, v238
	v_add_u32_e32 v104, 0x8000, v238
	v_add_u32_e32 v108, 0x10000, v238
	v_add_u32_e32 v112, 0x18000, v238
	s_waitcnt lgkmcnt(0)
	s_barrier
	global_load_dwordx4 v[100:103], v100, s[100:101] offset:256
	global_load_dwordx4 v[104:107], v104, s[100:101] offset:256
	global_load_dwordx4 v[108:111], v108, s[100:101] offset:256
	global_load_dwordx4 v[112:115], v112, s[100:101] offset:256
	s_and_b64 vcc, exec, s[4:5]
	s_cbranch_vccnz .Lat_pv1
	ds_read_b128 v[208:211], v187
	ds_read_b128 v[212:215], v187 offset:64
	ds_read_b128 v[36:39], v201
	ds_read_b128 v[40:43], v201 offset:2304
	ds_read_b128 v[44:47], v201 offset:4608
	ds_read_b128 v[48:51], v201 offset:6912
	ds_read_b128 v[52:55], v201 offset:9216
	ds_read_b128 v[56:59], v201 offset:11520
	ds_read_b128 v[60:63], v201 offset:13824
	ds_read_b128 v[64:67], v201 offset:16128
	s_waitcnt lgkmcnt(7)
	v_mfma_f32_16x16x32_bf16 v[176:179], v[36:39], v[208:211], v[176:179]
	ds_read_b128 v[68:71], v201 offset:18432
	s_waitcnt lgkmcnt(7)
	v_mfma_f32_16x16x32_bf16 v[172:175], v[40:43], v[208:211], v[172:175]
	ds_read_b128 v[72:75], v201 offset:20736
	s_waitcnt lgkmcnt(7)
	v_mfma_f32_16x16x32_bf16 v[168:171], v[44:47], v[208:211], v[168:171]
	ds_read_b128 v[76:79], v201 offset:23040
	s_waitcnt lgkmcnt(7)
	v_mfma_f32_16x16x32_bf16 v[164:167], v[48:51], v[208:211], v[164:167]
	ds_read_b128 v[80:83], v201 offset:25344
	s_waitcnt lgkmcnt(7)
	v_mfma_f32_16x16x32_bf16 v[160:163], v[52:55], v[208:211], v[160:163]
	ds_read_b128 v[84:87], v201 offset:27648
	s_waitcnt lgkmcnt(7)
	v_mfma_f32_16x16x32_bf16 v[156:159], v[56:59], v[208:211], v[156:159]
	ds_read_b128 v[88:91], v201 offset:29952
	s_waitcnt lgkmcnt(7)
	v_mfma_f32_16x16x32_bf16 v[152:155], v[60:63], v[208:211], v[152:155]
	ds_read_b128 v[92:95], v201 offset:32256
	s_waitcnt lgkmcnt(7)
	v_mfma_f32_16x16x32_bf16 v[148:151], v[64:67], v[208:211], v[148:151]
	ds_read_b128 v[96:99], v201 offset:34560
	s_waitcnt lgkmcnt(7)
	v_mfma_f32_16x16x32_bf16 v[144:147], v[68:71], v[208:211], v[144:147]
	ds_read_b128 v[36:39], v201 offset:64
	s_waitcnt lgkmcnt(7)
	v_mfma_f32_16x16x32_bf16 v[140:143], v[72:75], v[208:211], v[140:143]
	ds_read_b128 v[40:43], v201 offset:2368
	s_waitcnt lgkmcnt(7)
	v_mfma_f32_16x16x32_bf16 v[136:139], v[76:79], v[208:211], v[136:139]
	ds_read_b128 v[44:47], v201 offset:4672
	s_waitcnt lgkmcnt(7)
	v_mfma_f32_16x16x32_bf16 v[132:135], v[80:83], v[208:211], v[132:135]
	ds_read_b128 v[48:51], v201 offset:6976
	s_waitcnt lgkmcnt(7)
	v_mfma_f32_16x16x32_bf16 v[128:131], v[84:87], v[208:211], v[128:131]
	ds_read_b128 v[52:55], v201 offset:9280
	s_waitcnt lgkmcnt(7)
	v_mfma_f32_16x16x32_bf16 v[124:127], v[88:91], v[208:211], v[124:127]
	ds_read_b128 v[56:59], v201 offset:11584
	s_waitcnt lgkmcnt(7)
	v_mfma_f32_16x16x32_bf16 v[120:123], v[92:95], v[208:211], v[120:123]
	ds_read_b128 v[60:63], v201 offset:13888
	s_waitcnt lgkmcnt(7)
	v_mfma_f32_16x16x32_bf16 v[116:119], v[96:99], v[208:211], v[116:119]
	ds_read_b128 v[64:67], v201 offset:16192
	s_waitcnt lgkmcnt(7)
	v_mfma_f32_16x16x32_bf16 v[176:179], v[36:39], v[212:215], v[176:179]
	ds_read_b128 v[68:71], v201 offset:18496
	s_waitcnt lgkmcnt(7)
	v_mfma_f32_16x16x32_bf16 v[172:175], v[40:43], v[212:215], v[172:175]
	ds_read_b128 v[72:75], v201 offset:20800
	s_waitcnt lgkmcnt(7)
	v_mfma_f32_16x16x32_bf16 v[168:171], v[44:47], v[212:215], v[168:171]
	ds_read_b128 v[76:79], v201 offset:23104
	s_waitcnt lgkmcnt(7)
	v_mfma_f32_16x16x32_bf16 v[164:167], v[48:51], v[212:215], v[164:167]
	ds_read_b128 v[80:83], v201 offset:25408
	s_waitcnt lgkmcnt(7)
	v_mfma_f32_16x16x32_bf16 v[160:163], v[52:55], v[212:215], v[160:163]
	ds_read_b128 v[84:87], v201 offset:27712
	s_waitcnt lgkmcnt(7)
	v_mfma_f32_16x16x32_bf16 v[156:159], v[56:59], v[212:215], v[156:159]
	ds_read_b128 v[88:91], v201 offset:30016
	s_waitcnt lgkmcnt(7)
	v_mfma_f32_16x16x32_bf16 v[152:155], v[60:63], v[212:215], v[152:155]
	ds_read_b128 v[92:95], v201 offset:32320
	s_waitcnt lgkmcnt(7)
	v_mfma_f32_16x16x32_bf16 v[148:151], v[64:67], v[212:215], v[148:151]
	ds_read_b128 v[96:99], v201 offset:34624
	s_waitcnt lgkmcnt(7)
	v_mfma_f32_16x16x32_bf16 v[144:147], v[68:71], v[212:215], v[144:147]
	s_waitcnt lgkmcnt(6)
	v_mfma_f32_16x16x32_bf16 v[140:143], v[72:75], v[212:215], v[140:143]
	s_waitcnt lgkmcnt(5)
	v_mfma_f32_16x16x32_bf16 v[136:139], v[76:79], v[212:215], v[136:139]
	s_waitcnt lgkmcnt(4)
	v_mfma_f32_16x16x32_bf16 v[132:135], v[80:83], v[212:215], v[132:135]
	s_waitcnt lgkmcnt(3)
	v_mfma_f32_16x16x32_bf16 v[128:131], v[84:87], v[212:215], v[128:131]
	s_waitcnt lgkmcnt(2)
	v_mfma_f32_16x16x32_bf16 v[124:127], v[88:91], v[212:215], v[124:127]
	s_waitcnt lgkmcnt(1)
	v_mfma_f32_16x16x32_bf16 v[120:123], v[92:95], v[212:215], v[120:123]
	s_waitcnt lgkmcnt(0)
	v_mfma_f32_16x16x32_bf16 v[116:119], v[96:99], v[212:215], v[116:119]
; #define LAS __attribute__((address_space(3)))
; #define LOADV(i) do { _Pragma("unroll") for (int j = 0; j < 4; ++j) st[j] = *(const u32x4*)(vbase + (j * 64 * 256 + (i) * 64) + voff); } while (0)
; #define STOREV() do { _Pragma("unroll") for (int j = 0; j < 4; ++j) *(LAS u32x4*)(vst + j * 64 * 144) = st[j]; } while (0)
; __device__ __forceinline__ void ph_attn(const Params& p, LAS unsigned char* lds) {
;     ...
; #pragma unroll 1
;         for (int i = 0; i < 4; ++i) {
;             __syncthreads(); STOREV(); __syncthreads();
;             if (i < 3) LOADV(i + 1);
;             if (active) {
; #pragma unroll
;                 for (int ks = 0; ks < 2; ++ks) {
;                     const bf16x8 pf = *(const LAS bf16x8*)(pw + fq * 8 + i * 128 + ks * 64);
; #pragma unroll
;                     for (int dt = 0; dt < 16; ++dt) {
;                         const bf16x8 vf = *(const LAS bf16x8*)(vrd + dt * 16 * 144 + ks * 64);
;                         oa[dt] = __builtin_amdgcn_mfma_f32_16x16x32_bf16(vf, pf, oa[dt], 0, 0, 0);
;                     }
;                 }
;             }
;         }
.Lat_pv1:
	s_waitcnt lgkmcnt(0)
	s_barrier
	s_waitcnt vmcnt(7)
	ds_write_b128 v199, v[240:243]
	s_waitcnt vmcnt(6)
	ds_write_b128 v199, v[244:247] offset:9216
	s_waitcnt vmcnt(5)
	ds_write_b128 v199, v[248:251] offset:18432
	s_waitcnt vmcnt(4)
	ds_write_b128 v199, v[252:255] offset:27648
	v_mov_b32_e32 v240, v238
	v_add_u32_e32 v244, 0x8000, v238
	v_add_u32_e32 v248, 0x10000, v238
	v_add_u32_e32 v252, 0x18000, v238
	s_waitcnt lgkmcnt(0)
	s_barrier
	global_load_dwordx4 v[240:243], v240, s[100:101] offset:384
	global_load_dwordx4 v[244:247], v244, s[100:101] offset:384
	global_load_dwordx4 v[248:251], v248, s[100:101] offset:384
	global_load_dwordx4 v[252:255], v252, s[100:101] offset:384
	s_and_b64 vcc, exec, s[4:5]
	s_cbranch_vccnz .Lat_pv2
	ds_read_b128 v[208:211], v187 offset:128
	ds_read_b128 v[212:215], v187 offset:192
	ds_read_b128 v[36:39], v201
	ds_read_b128 v[40:43], v201 offset:2304
	ds_read_b128 v[44:47], v201 offset:4608
	ds_read_b128 v[48:51], v201 offset:6912
	ds_read_b128 v[52:55], v201 offset:9216
	ds_read_b128 v[56:59], v201 offset:11520
	ds_read_b128 v[60:63], v201 offset:13824
	ds_read_b128 v[64:67], v201 offset:16128
	s_waitcnt lgkmcnt(7)
	v_mfma_f32_16x16x32_bf16 v[176:179], v[36:39], v[208:211], v[176:179]
	ds_read_b128 v[68:71], v201 offset:18432
	s_waitcnt lgkmcnt(7)
	v_mfma_f32_16x16x32_bf16 v[172:175], v[40:43], v[208:211], v[172:175]
	ds_read_b128 v[72:75], v201 offset:20736
	s_waitcnt lgkmcnt(7)
	v_mfma_f32_16x16x32_bf16 v[168:171], v[44:47], v[208:211], v[168:171]
	ds_read_b128 v[76:79], v201 offset:23040
	s_waitcnt lgkmcnt(7)
	v_mfma_f32_16x16x32_bf16 v[164:167], v[48:51], v[208:211], v[164:167]
	ds_read_b128 v[80:83], v201 offset:25344
	s_waitcnt lgkmcnt(7)
	v_mfma_f32_16x16x32_bf16 v[160:163], v[52:55], v[208:211], v[160:163]
	ds_read_b128 v[84:87], v201 offset:27648
	s_waitcnt lgkmcnt(7)
	v_mfma_f32_16x16x32_bf16 v[156:159], v[56:59], v[208:211], v[156:159]
	ds_read_b128 v[88:91], v201 offset:29952
	s_waitcnt lgkmcnt(7)
	v_mfma_f32_16x16x32_bf16 v[152:155], v[60:63], v[208:211], v[152:155]
	ds_read_b128 v[92:95], v201 offset:32256
	s_waitcnt lgkmcnt(7)
	v_mfma_f32_16x16x32_bf16 v[148:151], v[64:67], v[208:211], v[148:151]
	ds_read_b128 v[96:99], v201 offset:34560
	s_waitcnt lgkmcnt(7)
	v_mfma_f32_16x16x32_bf16 v[144:147], v[68:71], v[208:211], v[144:147]
	ds_read_b128 v[36:39], v201 offset:64
	s_waitcnt lgkmcnt(7)
	v_mfma_f32_16x16x32_bf16 v[140:143], v[72:75], v[208:211], v[140:143]
	ds_read_b128 v[40:43], v201 offset:2368
	s_waitcnt lgkmcnt(7)
	v_mfma_f32_16x16x32_bf16 v[136:139], v[76:79], v[208:211], v[136:139]
	ds_read_b128 v[44:47], v201 offset:4672
	s_waitcnt lgkmcnt(7)
	v_mfma_f32_16x16x32_bf16 v[132:135], v[80:83], v[208:211], v[132:135]
	ds_read_b128 v[48:51], v201 offset:6976
	s_waitcnt lgkmcnt(7)
	v_mfma_f32_16x16x32_bf16 v[128:131], v[84:87], v[208:211], v[128:131]
	ds_read_b128 v[52:55], v201 offset:9280
	s_waitcnt lgkmcnt(7)
	v_mfma_f32_16x16x32_bf16 v[124:127], v[88:91], v[208:211], v[124:127]
	ds_read_b128 v[56:59], v201 offset:11584
	s_waitcnt lgkmcnt(7)
	v_mfma_f32_16x16x32_bf16 v[120:123], v[92:95], v[208:211], v[120:123]
	ds_read_b128 v[60:63], v201 offset:13888
	s_waitcnt lgkmcnt(7)
	v_mfma_f32_16x16x32_bf16 v[116:119], v[96:99], v[208:211], v[116:119]
	ds_read_b128 v[64:67], v201 offset:16192
	s_waitcnt lgkmcnt(7)
	v_mfma_f32_16x16x32_bf16 v[176:179], v[36:39], v[212:215], v[176:179]
	ds_read_b128 v[68:71], v201 offset:18496
	s_waitcnt lgkmcnt(7)
	v_mfma_f32_16x16x32_bf16 v[172:175], v[40:43], v[212:215], v[172:175]
	ds_read_b128 v[72:75], v201 offset:20800
	s_waitcnt lgkmcnt(7)
	v_mfma_f32_16x16x32_bf16 v[168:171], v[44:47], v[212:215], v[168:171]
	ds_read_b128 v[76:79], v201 offset:23104
	s_waitcnt lgkmcnt(7)
	v_mfma_f32_16x16x32_bf16 v[164:167], v[48:51], v[212:215], v[164:167]
	ds_read_b128 v[80:83], v201 offset:25408
	s_waitcnt lgkmcnt(7)
	v_mfma_f32_16x16x32_bf16 v[160:163], v[52:55], v[212:215], v[160:163]
	ds_read_b128 v[84:87], v201 offset:27712
	s_waitcnt lgkmcnt(7)
	v_mfma_f32_16x16x32_bf16 v[156:159], v[56:59], v[212:215], v[156:159]
	ds_read_b128 v[88:91], v201 offset:30016
	s_waitcnt lgkmcnt(7)
	v_mfma_f32_16x16x32_bf16 v[152:155], v[60:63], v[212:215], v[152:155]
	ds_read_b128 v[92:95], v201 offset:32320
	s_waitcnt lgkmcnt(7)
	v_mfma_f32_16x16x32_bf16 v[148:151], v[64:67], v[212:215], v[148:151]
	ds_read_b128 v[96:99], v201 offset:34624
	s_waitcnt lgkmcnt(7)
	v_mfma_f32_16x16x32_bf16 v[144:147], v[68:71], v[212:215], v[144:147]
	s_waitcnt lgkmcnt(6)
	v_mfma_f32_16x16x32_bf16 v[140:143], v[72:75], v[212:215], v[140:143]
	s_waitcnt lgkmcnt(5)
	v_mfma_f32_16x16x32_bf16 v[136:139], v[76:79], v[212:215], v[136:139]
	s_waitcnt lgkmcnt(4)
	v_mfma_f32_16x16x32_bf16 v[132:135], v[80:83], v[212:215], v[132:135]
	s_waitcnt lgkmcnt(3)
	v_mfma_f32_16x16x32_bf16 v[128:131], v[84:87], v[212:215], v[128:131]
	s_waitcnt lgkmcnt(2)
	v_mfma_f32_16x16x32_bf16 v[124:127], v[88:91], v[212:215], v[124:127]
	s_waitcnt lgkmcnt(1)
	v_mfma_f32_16x16x32_bf16 v[120:123], v[92:95], v[212:215], v[120:123]
	s_waitcnt lgkmcnt(0)
	v_mfma_f32_16x16x32_bf16 v[116:119], v[96:99], v[212:215], v[116:119]
; #define LAS __attribute__((address_space(3)))
; #define LOADV(i) do { _Pragma("unroll") for (int j = 0; j < 4; ++j) st[j] = *(const u32x4*)(vbase + (j * 64 * 256 + (i) * 64) + voff); } while (0)
; #define STOREV() do { _Pragma("unroll") for (int j = 0; j < 4; ++j) *(LAS u32x4*)(vst + j * 64 * 144) = st[j]; } while (0)
; __device__ __forceinline__ void ph_attn(const Params& p, LAS unsigned char* lds) {
;     ...
; #pragma unroll 1
;         for (int i = 0; i < 4; ++i) {
;             __syncthreads(); STOREV(); __syncthreads();
;             if (i < 3) LOADV(i + 1);
;             if (active) {
; #pragma unroll
;                 for (int ks = 0; ks < 2; ++ks) {
;                     const bf16x8 pf = *(const LAS bf16x8*)(pw + fq * 8 + i * 128 + ks * 64);
; #pragma unroll
;                     for (int dt = 0; dt < 16; ++dt) {
;                         const bf16x8 vf = *(const LAS bf16x8*)(vrd + dt * 16 * 144 + ks * 64);
;                         oa[dt] = __builtin_amdgcn_mfma_f32_16x16x32_bf16(vf, pf, oa[dt], 0, 0, 0);
;                     }
;                 }
;             }
;         }
.Lat_pv2:
	s_waitcnt lgkmcnt(0)
	s_barrier
	s_waitcnt vmcnt(7)
	ds_write_b128 v199, v[100:103]
	s_waitcnt vmcnt(6)
	ds_write_b128 v199, v[104:107] offset:9216
	s_waitcnt vmcnt(5)
	ds_write_b128 v199, v[108:111] offset:18432
	s_waitcnt vmcnt(4)
	ds_write_b128 v199, v[112:115] offset:27648
	s_waitcnt lgkmcnt(0)
	s_barrier
	s_and_b64 vcc, exec, s[4:5]
	s_cbranch_vccnz .Lat_pv3
	ds_read_b128 v[208:211], v187 offset:256
	ds_read_b128 v[212:215], v187 offset:320
	ds_read_b128 v[36:39], v201
	ds_read_b128 v[40:43], v201 offset:2304
	ds_read_b128 v[44:47], v201 offset:4608
	ds_read_b128 v[48:51], v201 offset:6912
	ds_read_b128 v[52:55], v201 offset:9216
	ds_read_b128 v[56:59], v201 offset:11520
	ds_read_b128 v[60:63], v201 offset:13824
	ds_read_b128 v[64:67], v201 offset:16128
	s_waitcnt lgkmcnt(7)
	v_mfma_f32_16x16x32_bf16 v[176:179], v[36:39], v[208:211], v[176:179]
	ds_read_b128 v[68:71], v201 offset:18432
	s_waitcnt lgkmcnt(7)
	v_mfma_f32_16x16x32_bf16 v[172:175], v[40:43], v[208:211], v[172:175]
	ds_read_b128 v[72:75], v201 offset:20736
	s_waitcnt lgkmcnt(7)
	v_mfma_f32_16x16x32_bf16 v[168:171], v[44:47], v[208:211], v[168:171]
	ds_read_b128 v[76:79], v201 offset:23040
	s_waitcnt lgkmcnt(7)
	v_mfma_f32_16x16x32_bf16 v[164:167], v[48:51], v[208:211], v[164:167]
	ds_read_b128 v[80:83], v201 offset:25344
	s_waitcnt lgkmcnt(7)
	v_mfma_f32_16x16x32_bf16 v[160:163], v[52:55], v[208:211], v[160:163]
	ds_read_b128 v[84:87], v201 offset:27648
	s_waitcnt lgkmcnt(7)
	v_mfma_f32_16x16x32_bf16 v[156:159], v[56:59], v[208:211], v[156:159]
	ds_read_b128 v[88:91], v201 offset:29952
	s_waitcnt lgkmcnt(7)
	v_mfma_f32_16x16x32_bf16 v[152:155], v[60:63], v[208:211], v[152:155]
	ds_read_b128 v[92:95], v201 offset:32256
	s_waitcnt lgkmcnt(7)
	v_mfma_f32_16x16x32_bf16 v[148:151], v[64:67], v[208:211], v[148:151]
	ds_read_b128 v[96:99], v201 offset:34560
	s_waitcnt lgkmcnt(7)
	v_mfma_f32_16x16x32_bf16 v[144:147], v[68:71], v[208:211], v[144:147]
	ds_read_b128 v[36:39], v201 offset:64
	s_waitcnt lgkmcnt(7)
	v_mfma_f32_16x16x32_bf16 v[140:143], v[72:75], v[208:211], v[140:143]
	ds_read_b128 v[40:43], v201 offset:2368
	s_waitcnt lgkmcnt(7)
	v_mfma_f32_16x16x32_bf16 v[136:139], v[76:79], v[208:211], v[136:139]
	ds_read_b128 v[44:47], v201 offset:4672
	s_waitcnt lgkmcnt(7)
	v_mfma_f32_16x16x32_bf16 v[132:135], v[80:83], v[208:211], v[132:135]
	ds_read_b128 v[48:51], v201 offset:6976
	s_waitcnt lgkmcnt(7)
	v_mfma_f32_16x16x32_bf16 v[128:131], v[84:87], v[208:211], v[128:131]
	ds_read_b128 v[52:55], v201 offset:9280
	s_waitcnt lgkmcnt(7)
	v_mfma_f32_16x16x32_bf16 v[124:127], v[88:91], v[208:211], v[124:127]
	ds_read_b128 v[56:59], v201 offset:11584
	s_waitcnt lgkmcnt(7)
	v_mfma_f32_16x16x32_bf16 v[120:123], v[92:95], v[208:211], v[120:123]
	ds_read_b128 v[60:63], v201 offset:13888
	s_waitcnt lgkmcnt(7)
	v_mfma_f32_16x16x32_bf16 v[116:119], v[96:99], v[208:211], v[116:119]
	ds_read_b128 v[64:67], v201 offset:16192
	s_waitcnt lgkmcnt(7)
	v_mfma_f32_16x16x32_bf16 v[176:179], v[36:39], v[212:215], v[176:179]
	ds_read_b128 v[68:71], v201 offset:18496
	s_waitcnt lgkmcnt(7)
	v_mfma_f32_16x16x32_bf16 v[172:175], v[40:43], v[212:215], v[172:175]
	ds_read_b128 v[72:75], v201 offset:20800
	s_waitcnt lgkmcnt(7)
	v_mfma_f32_16x16x32_bf16 v[168:171], v[44:47], v[212:215], v[168:171]
	ds_read_b128 v[76:79], v201 offset:23104
	s_waitcnt lgkmcnt(7)
	v_mfma_f32_16x16x32_bf16 v[164:167], v[48:51], v[212:215], v[164:167]
	ds_read_b128 v[80:83], v201 offset:25408
	s_waitcnt lgkmcnt(7)
	v_mfma_f32_16x16x32_bf16 v[160:163], v[52:55], v[212:215], v[160:163]
	ds_read_b128 v[84:87], v201 offset:27712
	s_waitcnt lgkmcnt(7)
	v_mfma_f32_16x16x32_bf16 v[156:159], v[56:59], v[212:215], v[156:159]
	ds_read_b128 v[88:91], v201 offset:30016
	s_waitcnt lgkmcnt(7)
	v_mfma_f32_16x16x32_bf16 v[152:155], v[60:63], v[212:215], v[152:155]
	ds_read_b128 v[92:95], v201 offset:32320
	s_waitcnt lgkmcnt(7)
	v_mfma_f32_16x16x32_bf16 v[148:151], v[64:67], v[212:215], v[148:151]
	ds_read_b128 v[96:99], v201 offset:34624
	s_waitcnt lgkmcnt(7)
	v_mfma_f32_16x16x32_bf16 v[144:147], v[68:71], v[212:215], v[144:147]
	s_waitcnt lgkmcnt(6)
	v_mfma_f32_16x16x32_bf16 v[140:143], v[72:75], v[212:215], v[140:143]
	s_waitcnt lgkmcnt(5)
	v_mfma_f32_16x16x32_bf16 v[136:139], v[76:79], v[212:215], v[136:139]
	s_waitcnt lgkmcnt(4)
	v_mfma_f32_16x16x32_bf16 v[132:135], v[80:83], v[212:215], v[132:135]
	s_waitcnt lgkmcnt(3)
	v_mfma_f32_16x16x32_bf16 v[128:131], v[84:87], v[212:215], v[128:131]
	s_waitcnt lgkmcnt(2)
	v_mfma_f32_16x16x32_bf16 v[124:127], v[88:91], v[212:215], v[124:127]
	s_waitcnt lgkmcnt(1)
	v_mfma_f32_16x16x32_bf16 v[120:123], v[92:95], v[212:215], v[120:123]
	s_waitcnt lgkmcnt(0)
	v_mfma_f32_16x16x32_bf16 v[116:119], v[96:99], v[212:215], v[116:119]
; #define LAS __attribute__((address_space(3)))
; #define LOADV(i) do { _Pragma("unroll") for (int j = 0; j < 4; ++j) st[j] = *(const u32x4*)(vbase + (j * 64 * 256 + (i) * 64) + voff); } while (0)
; #define STOREV() do { _Pragma("unroll") for (int j = 0; j < 4; ++j) *(LAS u32x4*)(vst + j * 64 * 144) = st[j]; } while (0)
; __device__ __forceinline__ void ph_attn(const Params& p, LAS unsigned char* lds) {
;     ...
; #pragma unroll 1
;         for (int i = 0; i < 4; ++i) {
;             __syncthreads(); STOREV(); __syncthreads();
;             if (i < 3) LOADV(i + 1);
;             if (active) {
; #pragma unroll
;                 for (int ks = 0; ks < 2; ++ks) {
;                     const bf16x8 pf = *(const LAS bf16x8*)(pw + fq * 8 + i * 128 + ks * 64);
; #pragma unroll
;                     for (int dt = 0; dt < 16; ++dt) {
;                         const bf16x8 vf = *(const LAS bf16x8*)(vrd + dt * 16 * 144 + ks * 64);
;                         oa[dt] = __builtin_amdgcn_mfma_f32_16x16x32_bf16(vf, pf, oa[dt], 0, 0, 0);
;                     }
;                 }
;             }
;         }
.Lat_pv3:
	s_waitcnt lgkmcnt(0)
	s_barrier
	s_waitcnt vmcnt(3)
	ds_write_b128 v199, v[240:243]
	s_waitcnt vmcnt(2)
	ds_write_b128 v199, v[244:247] offset:9216
	s_waitcnt vmcnt(1)
	ds_write_b128 v199, v[248:251] offset:18432
	s_waitcnt vmcnt(0)
	ds_write_b128 v199, v[252:255] offset:27648
	s_waitcnt lgkmcnt(0)
	s_barrier
	s_and_b64 vcc, exec, s[4:5]
	s_cbranch_vccnz .LBB0_1108
	ds_read_b128 v[208:211], v187 offset:384
	ds_read_b128 v[212:215], v187 offset:448
	ds_read_b128 v[36:39], v201
	ds_read_b128 v[40:43], v201 offset:2304
	ds_read_b128 v[44:47], v201 offset:4608
	ds_read_b128 v[48:51], v201 offset:6912
	ds_read_b128 v[52:55], v201 offset:9216
	ds_read_b128 v[56:59], v201 offset:11520
	ds_read_b128 v[60:63], v201 offset:13824
	ds_read_b128 v[64:67], v201 offset:16128
	s_waitcnt lgkmcnt(7)
	v_mfma_f32_16x16x32_bf16 v[176:179], v[36:39], v[208:211], v[176:179]
	ds_read_b128 v[68:71], v201 offset:18432
	s_waitcnt lgkmcnt(7)
	v_mfma_f32_16x16x32_bf16 v[172:175], v[40:43], v[208:211], v[172:175]
	ds_read_b128 v[72:75], v201 offset:20736
	s_waitcnt lgkmcnt(7)
	v_mfma_f32_16x16x32_bf16 v[168:171], v[44:47], v[208:211], v[168:171]
	ds_read_b128 v[76:79], v201 offset:23040
	s_waitcnt lgkmcnt(7)
	v_mfma_f32_16x16x32_bf16 v[164:167], v[48:51], v[208:211], v[164:167]
	ds_read_b128 v[80:83], v201 offset:25344
	s_waitcnt lgkmcnt(7)
	v_mfma_f32_16x16x32_bf16 v[160:163], v[52:55], v[208:211], v[160:163]
	ds_read_b128 v[84:87], v201 offset:27648
	s_waitcnt lgkmcnt(7)
	v_mfma_f32_16x16x32_bf16 v[156:159], v[56:59], v[208:211], v[156:159]
	ds_read_b128 v[88:91], v201 offset:29952
	s_waitcnt lgkmcnt(7)
	v_mfma_f32_16x16x32_bf16 v[152:155], v[60:63], v[208:211], v[152:155]
	ds_read_b128 v[92:95], v201 offset:32256
	s_waitcnt lgkmcnt(7)
	v_mfma_f32_16x16x32_bf16 v[148:151], v[64:67], v[208:211], v[148:151]
	ds_read_b128 v[96:99], v201 offset:34560
	s_waitcnt lgkmcnt(7)
	v_mfma_f32_16x16x32_bf16 v[144:147], v[68:71], v[208:211], v[144:147]
	ds_read_b128 v[36:39], v201 offset:64
	s_waitcnt lgkmcnt(7)
	v_mfma_f32_16x16x32_bf16 v[140:143], v[72:75], v[208:211], v[140:143]
	ds_read_b128 v[40:43], v201 offset:2368
	s_waitcnt lgkmcnt(7)
	v_mfma_f32_16x16x32_bf16 v[136:139], v[76:79], v[208:211], v[136:139]
	ds_read_b128 v[44:47], v201 offset:4672
	s_waitcnt lgkmcnt(7)
	v_mfma_f32_16x16x32_bf16 v[132:135], v[80:83], v[208:211], v[132:135]
	ds_read_b128 v[48:51], v201 offset:6976
	s_waitcnt lgkmcnt(7)
	v_mfma_f32_16x16x32_bf16 v[128:131], v[84:87], v[208:211], v[128:131]
	ds_read_b128 v[52:55], v201 offset:9280
	s_waitcnt lgkmcnt(7)
	v_mfma_f32_16x16x32_bf16 v[124:127], v[88:91], v[208:211], v[124:127]
	ds_read_b128 v[56:59], v201 offset:11584
	s_waitcnt lgkmcnt(7)
	v_mfma_f32_16x16x32_bf16 v[120:123], v[92:95], v[208:211], v[120:123]
	ds_read_b128 v[60:63], v201 offset:13888
	s_waitcnt lgkmcnt(7)
	v_mfma_f32_16x16x32_bf16 v[116:119], v[96:99], v[208:211], v[116:119]
	ds_read_b128 v[64:67], v201 offset:16192
	s_waitcnt lgkmcnt(7)
	v_mfma_f32_16x16x32_bf16 v[176:179], v[36:39], v[212:215], v[176:179]
	ds_read_b128 v[68:71], v201 offset:18496
	s_waitcnt lgkmcnt(7)
	v_mfma_f32_16x16x32_bf16 v[172:175], v[40:43], v[212:215], v[172:175]
	ds_read_b128 v[72:75], v201 offset:20800
	s_waitcnt lgkmcnt(7)
	v_mfma_f32_16x16x32_bf16 v[168:171], v[44:47], v[212:215], v[168:171]
	ds_read_b128 v[76:79], v201 offset:23104
	s_waitcnt lgkmcnt(7)
	v_mfma_f32_16x16x32_bf16 v[164:167], v[48:51], v[212:215], v[164:167]
	ds_read_b128 v[80:83], v201 offset:25408
	s_waitcnt lgkmcnt(7)
	v_mfma_f32_16x16x32_bf16 v[160:163], v[52:55], v[212:215], v[160:163]
	ds_read_b128 v[84:87], v201 offset:27712
	s_waitcnt lgkmcnt(7)
	v_mfma_f32_16x16x32_bf16 v[156:159], v[56:59], v[212:215], v[156:159]
	ds_read_b128 v[88:91], v201 offset:30016
	s_waitcnt lgkmcnt(7)
	v_mfma_f32_16x16x32_bf16 v[152:155], v[60:63], v[212:215], v[152:155]
	ds_read_b128 v[92:95], v201 offset:32320
	s_waitcnt lgkmcnt(7)
	v_mfma_f32_16x16x32_bf16 v[148:151], v[64:67], v[212:215], v[148:151]
	ds_read_b128 v[96:99], v201 offset:34624
	s_waitcnt lgkmcnt(7)
	v_mfma_f32_16x16x32_bf16 v[144:147], v[68:71], v[212:215], v[144:147]
	s_waitcnt lgkmcnt(6)
	v_mfma_f32_16x16x32_bf16 v[140:143], v[72:75], v[212:215], v[140:143]
	s_waitcnt lgkmcnt(5)
	v_mfma_f32_16x16x32_bf16 v[136:139], v[76:79], v[212:215], v[136:139]
	s_waitcnt lgkmcnt(4)
	v_mfma_f32_16x16x32_bf16 v[132:135], v[80:83], v[212:215], v[132:135]
	s_waitcnt lgkmcnt(3)
	v_mfma_f32_16x16x32_bf16 v[128:131], v[84:87], v[212:215], v[128:131]
	s_waitcnt lgkmcnt(2)
	v_mfma_f32_16x16x32_bf16 v[124:127], v[88:91], v[212:215], v[124:127]
	s_waitcnt lgkmcnt(1)
	v_mfma_f32_16x16x32_bf16 v[120:123], v[92:95], v[212:215], v[120:123]
	s_waitcnt lgkmcnt(0)
	v_mfma_f32_16x16x32_bf16 v[116:119], v[96:99], v[212:215], v[116:119]
